# stack5 + grid barrier: all waiters poll the TOP arrival counter (>= target) instead of the generation word
# baseline (speedup 1.0000x reference)
; DEVI unsigned xb_ld(unsigned* p)              { return __hip_atomic_load(p, __ATOMIC_RELAXED, __HIP_MEMORY_SCOPE_AGENT); }
; DEVI unsigned xb_add(unsigned* p, unsigned v) { return __hip_atomic_fetch_add(p, v, __ATOMIC_RELAXED, __HIP_MEMORY_SCOPE_AGENT); }
; #define XB_SPIN(cond, bar) do { unsigned _sp = 0; while (cond) { __builtin_amdgcn_s_sleep(1); \
;     if ((++_sp & 255u) == 0u) { if (xb_ld(&(bar)[XB_TMO])) break; if (_sp > XB_SPIN_CAP) { atomicAdd(&(bar)[XB_TMO], 1u); break; } } } } while (0)
; DEVI void xcd_barrier(unsigned* bar, volatile LAS unsigned* st) {
;     ...
;         const unsigned old = xb_add(&bar[XB_XSUB(x)], 1u);
;         const unsigned gen = old / nloc;
;         if (old + 1u == (gen + 1u) * nloc) {
;             __builtin_amdgcn_fence(__ATOMIC_RELEASE, "agent");
;             asm volatile("s_waitcnt vmcnt(0)" ::: "memory");
;             const unsigned og = xb_add(&bar[XB_TOP], 1u);
;             const unsigned tg = og / nx;
;             if (og + 1u == (tg + 1u) * nx) xb_add(&bar[XB_TOPGEN], 1u);
;             else XB_SPIN(xb_ld(&bar[XB_TOPGEN]) == tg, bar);
.LBB0_164:
	s_or_b64 exec, exec, s[6:7]
	v_cvt_f32_u32_e32 v4, v2
	s_waitcnt vmcnt(0)
	v_readfirstlane_b32 s4, v3
	v_sub_u32_e32 v3, 0, v2
	v_rcp_iflag_f32_e32 v4, v4
	v_add_u32_e32 v5, s4, v1
	v_mul_f32_e32 v4, 0x4f7ffffe, v4
	v_cvt_u32_f32_e32 v4, v4
	v_mul_lo_u32 v1, v3, v4
	v_mul_hi_u32 v1, v4, v1
	v_add_u32_e32 v1, v4, v1
	v_mul_hi_u32 v1, v5, v1
	v_mul_lo_u32 v3, v1, v2
	v_sub_u32_e32 v3, v5, v3
	v_add_u32_e32 v4, 1, v1
	v_cmp_ge_u32_e32 vcc, v3, v2
	s_nop 1
	v_cndmask_b32_e32 v1, v1, v4, vcc
	v_sub_u32_e32 v4, v3, v2
	v_cndmask_b32_e32 v3, v3, v4, vcc
	v_add_u32_e32 v4, 1, v1
	v_cmp_ge_u32_e32 vcc, v3, v2
	v_add_u32_e32 v3, 1, v5
	s_nop 0
	v_cndmask_b32_e32 v1, v1, v4, vcc
	v_mul_lo_u32 v4, v2, v1
	v_add_u32_e32 v2, v4, v2
	v_cmp_ne_u32_e32 vcc, v3, v2
	s_and_saveexec_b64 s[4:5], vcc
	s_xor_b64 s[4:5], exec, s[4:5]
	s_cbranch_execz .LBB0_182
	s_waitcnt lgkmcnt(0)
	v_mov_b32_e32 v250, 0x26ff4
	ds_read_b32 v250, v250
	v_add_u32_e32 v251, 1, v1
	s_waitcnt lgkmcnt(0)
	v_mul_lo_u32 v250, v250, v251
	s_add_u32 s10, s96, 0x6ff500
	s_addc_u32 s11, s97, 0
	v_mov_b32_e32 v0, 0
	global_load_dword v0, v0, s[10:11] offset:-256 sc1
	s_waitcnt vmcnt(0)
	v_cmp_lt_u32_e32 vcc, v0, v250
	s_and_saveexec_b64 s[6:7], vcc
	s_cbranch_execz .LBB0_181
	s_add_u32 s8, s96, 0x6fc200
	s_addc_u32 s9, s97, 0
	s_mov_b32 s22, 1
	s_mov_b64 s[12:13], 0
	v_mov_b32_e32 v0, 0
	s_branch .LBB0_168

; DEVI unsigned xb_ld(unsigned* p)              { return __hip_atomic_load(p, __ATOMIC_RELAXED, __HIP_MEMORY_SCOPE_AGENT); }
; #define XB_SPIN(cond, bar) do { unsigned _sp = 0; while (cond) { __builtin_amdgcn_s_sleep(1); \
;     if ((++_sp & 255u) == 0u) { if (xb_ld(&(bar)[XB_TMO])) break; if (_sp > XB_SPIN_CAP) { atomicAdd(&(bar)[XB_TMO], 1u); break; } } } } while (0)
; DEVI void xcd_barrier(unsigned* bar, volatile LAS unsigned* st) {
;     ...
;             else XB_SPIN(xb_ld(&bar[XB_TOPGEN]) == tg, bar);
.LBB0_172:
	global_load_dword v2, v0, s[10:11] offset:-256 sc1
	s_add_i32 s22, s22, 1
	s_mov_b64 s[18:19], -1
	s_waitcnt vmcnt(0)
	v_cmp_ge_u32_e32 vcc, v2, v250
	s_orn2_b64 s[16:17], vcc, exec
	s_branch .LBB0_167

; DEVI unsigned xb_ld(unsigned* p)              { return __hip_atomic_load(p, __ATOMIC_RELAXED, __HIP_MEMORY_SCOPE_AGENT); }
; DEVI unsigned xb_add(unsigned* p, unsigned v) { return __hip_atomic_fetch_add(p, v, __ATOMIC_RELAXED, __HIP_MEMORY_SCOPE_AGENT); }
; #define XB_SPIN(cond, bar) do { unsigned _sp = 0; while (cond) { __builtin_amdgcn_s_sleep(1); \
;     if ((++_sp & 255u) == 0u) { if (xb_ld(&(bar)[XB_TMO])) break; if (_sp > XB_SPIN_CAP) { atomicAdd(&(bar)[XB_TMO], 1u); break; } } } } while (0)
; DEVI void xcd_barrier(unsigned* bar, volatile LAS unsigned* st) {
;     ...
;             const unsigned og = xb_add(&bar[XB_TOP], 1u);
;             const unsigned tg = og / nx;
;             if (og + 1u == (tg + 1u) * nx) xb_add(&bar[XB_TOPGEN], 1u);
;             else XB_SPIN(xb_ld(&bar[XB_TOPGEN]) == tg, bar);
.LBB0_185:
	s_or_b64 exec, exec, s[6:7]
	v_cvt_f32_u32_e32 v3, v0
	s_waitcnt vmcnt(0)
	v_readfirstlane_b32 s4, v2
	s_add_u32 s6, s96, 0x6ff500
	s_addc_u32 s7, s97, 0
	v_rcp_iflag_f32_e32 v3, v3
	v_add_u32_e32 v1, s4, v1
	v_add_u32_e32 v4, 1, v1
	s_mov_b64 s[8:9], -1
	v_mul_f32_e32 v2, 0x4f7ffffe, v3
	v_cvt_u32_f32_e32 v2, v2
	v_sub_u32_e32 v3, 0, v0
	v_mul_lo_u32 v3, v3, v2
	v_mul_hi_u32 v3, v2, v3
	v_add_u32_e32 v2, v2, v3
	v_mul_hi_u32 v2, v1, v2
	v_mul_lo_u32 v3, v2, v0
	v_sub_u32_e32 v1, v1, v3
	v_add_u32_e32 v5, 1, v2
	v_cmp_ge_u32_e32 vcc, v1, v0
	v_sub_u32_e32 v3, v1, v0
	s_nop 0
	v_cndmask_b32_e32 v2, v2, v5, vcc
	v_cndmask_b32_e32 v1, v1, v3, vcc
	v_add_u32_e32 v3, 1, v2
	v_cmp_ge_u32_e32 vcc, v1, v0
	s_nop 1
	v_cndmask_b32_e32 v2, v2, v3, vcc
	v_mul_lo_u32 v1, v0, v2
	v_add_u32_e32 v0, v1, v0
	v_mov_b32_e32 v250, v0
	v_cmp_ne_u32_e32 vcc, v4, v0
	v_mov_b64_e32 v[0:1], s[6:7]
	s_and_saveexec_b64 s[4:5], vcc
	s_cbranch_execz .LBB0_197
	v_mov_b32_e32 v0, 0
	global_load_dword v1, v0, s[6:7] offset:-256 sc1
	s_mov_b64 s[12:13], 0
	s_waitcnt vmcnt(0)
	v_cmp_lt_u32_e32 vcc, v1, v250
	s_and_saveexec_b64 s[10:11], vcc
	s_cbranch_execz .LBB0_196
	s_add_u32 s8, s96, 0x6fc200
	s_addc_u32 s9, s97, 0
	s_mov_b32 s22, 1
	s_branch .LBB0_189

; DEVI unsigned xb_ld(unsigned* p)              { return __hip_atomic_load(p, __ATOMIC_RELAXED, __HIP_MEMORY_SCOPE_AGENT); }
; #define XB_SPIN(cond, bar) do { unsigned _sp = 0; while (cond) { __builtin_amdgcn_s_sleep(1); \
;     if ((++_sp & 255u) == 0u) { if (xb_ld(&(bar)[XB_TMO])) break; if (_sp > XB_SPIN_CAP) { atomicAdd(&(bar)[XB_TMO], 1u); break; } } } } while (0)
; DEVI void xcd_barrier(unsigned* bar, volatile LAS unsigned* st) {
;     ...
;             else XB_SPIN(xb_ld(&bar[XB_TOPGEN]) == tg, bar);
.LBB0_193:
	global_load_dword v1, v0, s[6:7] offset:-256 sc1
	s_add_i32 s22, s22, 1
	s_mov_b64 s[16:17], -1
	s_waitcnt vmcnt(0)
	v_cmp_ge_u32_e32 vcc, v1, v250
	s_orn2_b64 s[20:21], vcc, exec
	s_branch .LBB0_188

; DEVI unsigned xb_ld(unsigned* p)              { return __hip_atomic_load(p, __ATOMIC_RELAXED, __HIP_MEMORY_SCOPE_AGENT); }
; DEVI unsigned xb_add(unsigned* p, unsigned v) { return __hip_atomic_fetch_add(p, v, __ATOMIC_RELAXED, __HIP_MEMORY_SCOPE_AGENT); }
; #define XB_SPIN(cond, bar) do { unsigned _sp = 0; while (cond) { __builtin_amdgcn_s_sleep(1); \
;     if ((++_sp & 255u) == 0u) { if (xb_ld(&(bar)[XB_TMO])) break; if (_sp > XB_SPIN_CAP) { atomicAdd(&(bar)[XB_TMO], 1u); break; } } } } while (0)
; DEVI void xcd_barrier(unsigned* bar, volatile LAS unsigned* st) {
;     ...
;         const unsigned old = xb_add(&bar[XB_XSUB(x)], 1u);
;         const unsigned gen = old / nloc;
;         if (old + 1u == (gen + 1u) * nloc) {
;             __builtin_amdgcn_fence(__ATOMIC_RELEASE, "agent");
;             asm volatile("s_waitcnt vmcnt(0)" ::: "memory");
;             const unsigned og = xb_add(&bar[XB_TOP], 1u);
;             const unsigned tg = og / nx;
;             if (og + 1u == (tg + 1u) * nx) xb_add(&bar[XB_TOPGEN], 1u);
;             else XB_SPIN(xb_ld(&bar[XB_TOPGEN]) == tg, bar);
.LBB0_1461:
	s_or_b64 exec, exec, s[8:9]
	v_cvt_f32_u32_e32 v4, v2
	s_waitcnt vmcnt(0)
	v_readfirstlane_b32 s6, v3
	v_sub_u32_e32 v3, 0, v2
	v_rcp_iflag_f32_e32 v4, v4
	v_add_u32_e32 v5, s6, v1
	v_mul_f32_e32 v4, 0x4f7ffffe, v4
	v_cvt_u32_f32_e32 v4, v4
	v_mul_lo_u32 v1, v3, v4
	v_mul_hi_u32 v1, v4, v1
	v_add_u32_e32 v1, v4, v1
	v_mul_hi_u32 v1, v5, v1
	v_mul_lo_u32 v3, v1, v2
	v_sub_u32_e32 v3, v5, v3
	v_add_u32_e32 v4, 1, v1
	v_cmp_ge_u32_e32 vcc, v3, v2
	s_nop 1
	v_cndmask_b32_e32 v1, v1, v4, vcc
	v_sub_u32_e32 v4, v3, v2
	v_cndmask_b32_e32 v3, v3, v4, vcc
	v_add_u32_e32 v4, 1, v1
	v_cmp_ge_u32_e32 vcc, v3, v2
	v_add_u32_e32 v3, 1, v5
	s_nop 0
	v_cndmask_b32_e32 v1, v1, v4, vcc
	v_mul_lo_u32 v4, v2, v1
	v_add_u32_e32 v2, v4, v2
	v_cmp_ne_u32_e32 vcc, v3, v2
	s_and_saveexec_b64 s[6:7], vcc
	s_xor_b64 s[6:7], exec, s[6:7]
	s_cbranch_execz .LBB0_1475
	s_waitcnt lgkmcnt(0)
	v_mov_b32_e32 v250, 0x26ff4
	ds_read_b32 v250, v250
	v_add_u32_e32 v251, 1, v1
	s_waitcnt lgkmcnt(0)
	v_mul_lo_u32 v250, v250, v251
	s_add_u32 s12, s96, 0x6ff500
	s_addc_u32 s13, s97, 0
	v_mov_b32_e32 v0, 0
	global_load_dword v0, v0, s[12:13] offset:-256 sc1
	s_waitcnt vmcnt(0)
	v_cmp_lt_u32_e32 vcc, v0, v250
	s_and_saveexec_b64 s[8:9], vcc
	s_cbranch_execz .LBB0_1474
	s_add_u32 s10, s96, 0x6fc200
	s_addc_u32 s11, s97, 0
	s_mov_b32 s24, 1
	s_mov_b64 s[14:15], 0
	v_mov_b32_e32 v0, 0
	s_branch .LBB0_1465

; DEVI unsigned xb_ld(unsigned* p)              { return __hip_atomic_load(p, __ATOMIC_RELAXED, __HIP_MEMORY_SCOPE_AGENT); }
; #define XB_SPIN(cond, bar) do { unsigned _sp = 0; while (cond) { __builtin_amdgcn_s_sleep(1); \
;     if ((++_sp & 255u) == 0u) { if (xb_ld(&(bar)[XB_TMO])) break; if (_sp > XB_SPIN_CAP) { atomicAdd(&(bar)[XB_TMO], 1u); break; } } } } while (0)
; DEVI void xcd_barrier(unsigned* bar, volatile LAS unsigned* st) {
;     ...
;             else XB_SPIN(xb_ld(&bar[XB_TOPGEN]) == tg, bar);
.LBB0_1469:
	global_load_dword v2, v0, s[12:13] offset:-256 sc1
	s_add_i32 s24, s24, 1
	s_mov_b64 s[20:21], -1
	s_waitcnt vmcnt(0)
	v_cmp_ge_u32_e32 vcc, v2, v250
	s_orn2_b64 s[18:19], vcc, exec
	s_branch .LBB0_1464

; DEVI unsigned xb_ld(unsigned* p)              { return __hip_atomic_load(p, __ATOMIC_RELAXED, __HIP_MEMORY_SCOPE_AGENT); }
; DEVI unsigned xb_add(unsigned* p, unsigned v) { return __hip_atomic_fetch_add(p, v, __ATOMIC_RELAXED, __HIP_MEMORY_SCOPE_AGENT); }
; #define XB_SPIN(cond, bar) do { unsigned _sp = 0; while (cond) { __builtin_amdgcn_s_sleep(1); \
;     if ((++_sp & 255u) == 0u) { if (xb_ld(&(bar)[XB_TMO])) break; if (_sp > XB_SPIN_CAP) { atomicAdd(&(bar)[XB_TMO], 1u); break; } } } } while (0)
; DEVI void xcd_barrier(unsigned* bar, volatile LAS unsigned* st) {
;     ...
;             const unsigned og = xb_add(&bar[XB_TOP], 1u);
;             const unsigned tg = og / nx;
;             if (og + 1u == (tg + 1u) * nx) xb_add(&bar[XB_TOPGEN], 1u);
;             else XB_SPIN(xb_ld(&bar[XB_TOPGEN]) == tg, bar);
.LBB0_1478:
	s_or_b64 exec, exec, s[8:9]
	v_cvt_f32_u32_e32 v3, v0
	s_waitcnt vmcnt(0)
	v_readfirstlane_b32 s6, v2
	s_add_u32 s8, s96, 0x6ff500
	s_addc_u32 s9, s97, 0
	v_rcp_iflag_f32_e32 v3, v3
	v_add_u32_e32 v1, s6, v1
	v_add_u32_e32 v4, 1, v1
	s_mov_b64 s[10:11], -1
	v_mul_f32_e32 v2, 0x4f7ffffe, v3
	v_cvt_u32_f32_e32 v2, v2
	v_sub_u32_e32 v3, 0, v0
	v_mul_lo_u32 v3, v3, v2
	v_mul_hi_u32 v3, v2, v3
	v_add_u32_e32 v2, v2, v3
	v_mul_hi_u32 v2, v1, v2
	v_mul_lo_u32 v3, v2, v0
	v_sub_u32_e32 v1, v1, v3
	v_add_u32_e32 v5, 1, v2
	v_cmp_ge_u32_e32 vcc, v1, v0
	v_sub_u32_e32 v3, v1, v0
	s_nop 0
	v_cndmask_b32_e32 v2, v2, v5, vcc
	v_cndmask_b32_e32 v1, v1, v3, vcc
	v_add_u32_e32 v3, 1, v2
	v_cmp_ge_u32_e32 vcc, v1, v0
	s_nop 1
	v_cndmask_b32_e32 v2, v2, v3, vcc
	v_mul_lo_u32 v1, v0, v2
	v_add_u32_e32 v0, v1, v0
	v_mov_b32_e32 v250, v0
	v_cmp_ne_u32_e32 vcc, v4, v0
	v_mov_b64_e32 v[0:1], s[8:9]
	s_and_saveexec_b64 s[6:7], vcc
	s_cbranch_execz .LBB0_1490
	v_mov_b32_e32 v0, 0
	global_load_dword v1, v0, s[8:9] offset:-256 sc1
	s_mov_b64 s[14:15], 0
	s_waitcnt vmcnt(0)
	v_cmp_lt_u32_e32 vcc, v1, v250
	s_and_saveexec_b64 s[12:13], vcc
	s_cbranch_execz .LBB0_1489
	s_add_u32 s10, s96, 0x6fc200
	s_addc_u32 s11, s97, 0
	s_mov_b32 s24, 1
	s_branch .LBB0_1482

; DEVI unsigned xb_ld(unsigned* p)              { return __hip_atomic_load(p, __ATOMIC_RELAXED, __HIP_MEMORY_SCOPE_AGENT); }
; #define XB_SPIN(cond, bar) do { unsigned _sp = 0; while (cond) { __builtin_amdgcn_s_sleep(1); \
;     if ((++_sp & 255u) == 0u) { if (xb_ld(&(bar)[XB_TMO])) break; if (_sp > XB_SPIN_CAP) { atomicAdd(&(bar)[XB_TMO], 1u); break; } } } } while (0)
; DEVI void xcd_barrier(unsigned* bar, volatile LAS unsigned* st) {
;     ...
;             else XB_SPIN(xb_ld(&bar[XB_TOPGEN]) == tg, bar);
.LBB0_1486:
	global_load_dword v1, v0, s[8:9] offset:-256 sc1
	s_add_i32 s24, s24, 1
	s_mov_b64 s[18:19], -1
	s_waitcnt vmcnt(0)
	v_cmp_ge_u32_e32 vcc, v1, v250
	s_orn2_b64 s[22:23], vcc, exec
	s_branch .LBB0_1481

; DEVI unsigned xb_ld(unsigned* p)              { return __hip_atomic_load(p, __ATOMIC_RELAXED, __HIP_MEMORY_SCOPE_AGENT); }
; DEVI unsigned xb_add(unsigned* p, unsigned v) { return __hip_atomic_fetch_add(p, v, __ATOMIC_RELAXED, __HIP_MEMORY_SCOPE_AGENT); }
; #define XB_SPIN(cond, bar) do { unsigned _sp = 0; while (cond) { __builtin_amdgcn_s_sleep(1); \
;     if ((++_sp & 255u) == 0u) { if (xb_ld(&(bar)[XB_TMO])) break; if (_sp > XB_SPIN_CAP) { atomicAdd(&(bar)[XB_TMO], 1u); break; } } } } while (0)
; DEVI void xcd_barrier(unsigned* bar, volatile LAS unsigned* st) {
;     ...
;         const unsigned old = xb_add(&bar[XB_XSUB(x)], 1u);
;         const unsigned gen = old / nloc;
;         if (old + 1u == (gen + 1u) * nloc) {
;             __builtin_amdgcn_fence(__ATOMIC_RELEASE, "agent");
;             asm volatile("s_waitcnt vmcnt(0)" ::: "memory");
;             const unsigned og = xb_add(&bar[XB_TOP], 1u);
;             const unsigned tg = og / nx;
;             if (og + 1u == (tg + 1u) * nx) xb_add(&bar[XB_TOPGEN], 1u);
;             else XB_SPIN(xb_ld(&bar[XB_TOPGEN]) == tg, bar);
.LBB0_2768:
	s_or_b64 exec, exec, s[6:7]
	v_cvt_f32_u32_e32 v4, v2
	s_waitcnt vmcnt(0)
	v_readfirstlane_b32 s4, v3
	v_sub_u32_e32 v3, 0, v2
	v_rcp_iflag_f32_e32 v4, v4
	v_add_u32_e32 v5, s4, v1
	v_mul_f32_e32 v4, 0x4f7ffffe, v4
	v_cvt_u32_f32_e32 v4, v4
	v_mul_lo_u32 v1, v3, v4
	v_mul_hi_u32 v1, v4, v1
	v_add_u32_e32 v1, v4, v1
	v_mul_hi_u32 v1, v5, v1
	v_mul_lo_u32 v3, v1, v2
	v_sub_u32_e32 v3, v5, v3
	v_add_u32_e32 v4, 1, v1
	v_cmp_ge_u32_e32 vcc, v3, v2
	s_nop 1
	v_cndmask_b32_e32 v1, v1, v4, vcc
	v_sub_u32_e32 v4, v3, v2
	v_cndmask_b32_e32 v3, v3, v4, vcc
	v_add_u32_e32 v4, 1, v1
	v_cmp_ge_u32_e32 vcc, v3, v2
	v_add_u32_e32 v3, 1, v5
	s_nop 0
	v_cndmask_b32_e32 v1, v1, v4, vcc
	v_mul_lo_u32 v4, v2, v1
	v_add_u32_e32 v2, v4, v2
	v_cmp_ne_u32_e32 vcc, v3, v2
	s_and_saveexec_b64 s[4:5], vcc
	s_xor_b64 s[4:5], exec, s[4:5]
	s_cbranch_execz .LBB0_2782
	s_waitcnt lgkmcnt(0)
	v_mov_b32_e32 v250, 0x26ff4
	ds_read_b32 v250, v250
	v_add_u32_e32 v251, 1, v1
	s_waitcnt lgkmcnt(0)
	v_mul_lo_u32 v250, v250, v251
	s_add_u32 s10, s96, 0x6ff500
	s_addc_u32 s11, s97, 0
	v_mov_b32_e32 v0, 0
	global_load_dword v0, v0, s[10:11] offset:-256 sc1
	s_waitcnt vmcnt(0)
	v_cmp_lt_u32_e32 vcc, v0, v250
	s_and_saveexec_b64 s[6:7], vcc
	s_cbranch_execz .LBB0_2781
	s_add_u32 s8, s96, 0x6fc200
	s_addc_u32 s9, s97, 0
	s_mov_b32 s24, 1
	s_mov_b64 s[14:15], 0
	v_mov_b32_e32 v0, 0
	s_branch .LBB0_2772

; DEVI unsigned xb_ld(unsigned* p)              { return __hip_atomic_load(p, __ATOMIC_RELAXED, __HIP_MEMORY_SCOPE_AGENT); }
; #define XB_SPIN(cond, bar) do { unsigned _sp = 0; while (cond) { __builtin_amdgcn_s_sleep(1); \
;     if ((++_sp & 255u) == 0u) { if (xb_ld(&(bar)[XB_TMO])) break; if (_sp > XB_SPIN_CAP) { atomicAdd(&(bar)[XB_TMO], 1u); break; } } } } while (0)
; DEVI void xcd_barrier(unsigned* bar, volatile LAS unsigned* st) {
;     ...
;             else XB_SPIN(xb_ld(&bar[XB_TOPGEN]) == tg, bar);
.LBB0_2776:
	global_load_dword v2, v0, s[10:11] offset:-256 sc1
	s_add_i32 s24, s24, 1
	s_mov_b64 s[20:21], -1
	s_waitcnt vmcnt(0)
	v_cmp_ge_u32_e32 vcc, v2, v250
	s_orn2_b64 s[18:19], vcc, exec
	s_branch .LBB0_2771

; DEVI unsigned xb_ld(unsigned* p)              { return __hip_atomic_load(p, __ATOMIC_RELAXED, __HIP_MEMORY_SCOPE_AGENT); }
; DEVI unsigned xb_add(unsigned* p, unsigned v) { return __hip_atomic_fetch_add(p, v, __ATOMIC_RELAXED, __HIP_MEMORY_SCOPE_AGENT); }
; #define XB_SPIN(cond, bar) do { unsigned _sp = 0; while (cond) { __builtin_amdgcn_s_sleep(1); \
;     if ((++_sp & 255u) == 0u) { if (xb_ld(&(bar)[XB_TMO])) break; if (_sp > XB_SPIN_CAP) { atomicAdd(&(bar)[XB_TMO], 1u); break; } } } } while (0)
; DEVI void xcd_barrier(unsigned* bar, volatile LAS unsigned* st) {
;     ...
;             const unsigned og = xb_add(&bar[XB_TOP], 1u);
;             const unsigned tg = og / nx;
;             if (og + 1u == (tg + 1u) * nx) xb_add(&bar[XB_TOPGEN], 1u);
;             else XB_SPIN(xb_ld(&bar[XB_TOPGEN]) == tg, bar);
.LBB0_2785:
	s_or_b64 exec, exec, s[6:7]
	v_cvt_f32_u32_e32 v3, v0
	s_waitcnt vmcnt(0)
	v_readfirstlane_b32 s4, v2
	s_add_u32 s6, s96, 0x6ff500
	s_addc_u32 s7, s97, 0
	v_rcp_iflag_f32_e32 v3, v3
	v_add_u32_e32 v1, s4, v1
	v_add_u32_e32 v4, 1, v1
	s_mov_b64 s[8:9], -1
	v_mul_f32_e32 v2, 0x4f7ffffe, v3
	v_cvt_u32_f32_e32 v2, v2
	v_sub_u32_e32 v3, 0, v0
	v_mul_lo_u32 v3, v3, v2
	v_mul_hi_u32 v3, v2, v3
	v_add_u32_e32 v2, v2, v3
	v_mul_hi_u32 v2, v1, v2
	v_mul_lo_u32 v3, v2, v0
	v_sub_u32_e32 v1, v1, v3
	v_add_u32_e32 v5, 1, v2
	v_cmp_ge_u32_e32 vcc, v1, v0
	v_sub_u32_e32 v3, v1, v0
	s_nop 0
	v_cndmask_b32_e32 v2, v2, v5, vcc
	v_cndmask_b32_e32 v1, v1, v3, vcc
	v_add_u32_e32 v3, 1, v2
	v_cmp_ge_u32_e32 vcc, v1, v0
	s_nop 1
	v_cndmask_b32_e32 v2, v2, v3, vcc
	v_mul_lo_u32 v1, v0, v2
	v_add_u32_e32 v0, v1, v0
	v_mov_b32_e32 v250, v0
	v_cmp_ne_u32_e32 vcc, v4, v0
	v_mov_b64_e32 v[0:1], s[6:7]
	s_and_saveexec_b64 s[4:5], vcc
	s_cbranch_execz .LBB0_2797
	v_mov_b32_e32 v0, 0
	global_load_dword v1, v0, s[6:7] offset:-256 sc1
	s_mov_b64 s[14:15], 0
	s_waitcnt vmcnt(0)
	v_cmp_lt_u32_e32 vcc, v1, v250
	s_and_saveexec_b64 s[10:11], vcc
	s_cbranch_execz .LBB0_2796
	s_add_u32 s8, s96, 0x6fc200
	s_addc_u32 s9, s97, 0
	s_mov_b32 s24, 1
	s_branch .LBB0_2789

; DEVI unsigned xb_ld(unsigned* p)              { return __hip_atomic_load(p, __ATOMIC_RELAXED, __HIP_MEMORY_SCOPE_AGENT); }
; #define XB_SPIN(cond, bar) do { unsigned _sp = 0; while (cond) { __builtin_amdgcn_s_sleep(1); \
;     if ((++_sp & 255u) == 0u) { if (xb_ld(&(bar)[XB_TMO])) break; if (_sp > XB_SPIN_CAP) { atomicAdd(&(bar)[XB_TMO], 1u); break; } } } } while (0)
; DEVI void xcd_barrier(unsigned* bar, volatile LAS unsigned* st) {
;     ...
;             else XB_SPIN(xb_ld(&bar[XB_TOPGEN]) == tg, bar);
.LBB0_2793:
	global_load_dword v1, v0, s[6:7] offset:-256 sc1
	s_add_i32 s24, s24, 1
	s_mov_b64 s[18:19], -1
	s_waitcnt vmcnt(0)
	v_cmp_ge_u32_e32 vcc, v1, v250
	s_orn2_b64 s[22:23], vcc, exec
	s_branch .LBB0_2788
